# attention step: both blocks' max trees hoisted ahead of the first rescale check so the PV MFMAs spread evenly (uniform MFMA/VALU interleave)
# baseline (speedup 1.0000x reference)
; #define LAS __attribute__((address_space(3)))
; #define DMAT(kt, so) do { const unsigned rb_ = (unsigned)ROWBASE(kt); _Pragma("unroll") for (int r = 0; r < 3; ++r) if (wid + 8 * r < 22) \
;         __builtin_amdgcn_global_load_lds((const unsigned*)(dsrc[r] + (size_t)rb_ * dmul[r]), (LAS unsigned*)(lds + (so) + dlds[r]), 16, 0, 0); } while (0)
; __device__ __forceinline__ void attn_unit2(LAS unsigned char* lds, const bf16_t* __restrict__ Q, const bf16_t* __restrict__ KN, const bf16_t* __restrict__ KPE, ...
;     ...
;     for (int t = 0; t < ntiles; ++t) {
;         __builtin_amdgcn_sched_barrier(0);
;         f32x16 sa0 = {}, sa1 = {}, sb0 = {}, sb1 = {};
;         const LAS unsigned char* ka = lds + sc + ka_off;
; #pragma unroll
;         for (int ds = 0; ds < 6; ++ds) {
;             const bf16x8 k0 = *(const LAS bf16x8*)(ka + ds * 32);
;             const bf16x8 k1 = *(const LAS bf16x8*)(ka + 32 * KROW + ds * 32);
;             sa0 = __builtin_amdgcn_mfma_f32_32x32x16_bf16(k0, qa[ds], sa0, 0, 0, 0);
;             sa1 = __builtin_amdgcn_mfma_f32_32x32x16_bf16(k1, qa[ds], sa1, 0, 0, 0);
;             sb0 = __builtin_amdgcn_mfma_f32_32x32x16_bf16(k0, qb[ds], sb0, 0, 0, 0);
;             sb1 = __builtin_amdgcn_mfma_f32_32x32x16_bf16(k1, qb[ds], sb1, 0, 0, 0);
;         }
;         __builtin_amdgcn_sched_barrier(0);
;         if (t + 2 < ntiles) DMAT(t + 2, snn);
;         u32x4 pa[4], pb[4];
;     ...
;         SOFTMAX2(sa0, sa1, ma, la, oa0, oa1, pa);
;         SOFTMAX2(sb0, sb1, mb, lb, ob0, ob1, pb);
;     ...
;         const LAS unsigned char* va = lds + sc + va_off;
; #pragma unroll
;         for (int st = 0; st < 4; ++st) {
;             const bf16x8 v0 = *(const LAS bf16x8*)(va + st * 32);
;             const bf16x8 v1 = *(const LAS bf16x8*)(va + 32 * VROW + st * 32);
;             const bf16x8 fa = __builtin_bit_cast(bf16x8, pa[st]), fb = __builtin_bit_cast(bf16x8, pb[st]);
;             oa0 = __builtin_amdgcn_mfma_f32_32x32x16_bf16(v0, fa, oa0, 0, 0, 0);
;             oa1 = __builtin_amdgcn_mfma_f32_32x32x16_bf16(v1, fa, oa1, 0, 0, 0);
;             ob0 = __builtin_amdgcn_mfma_f32_32x32x16_bf16(v0, fb, ob0, 0, 0, 0);
;             ob1 = __builtin_amdgcn_mfma_f32_32x32x16_bf16(v1, fb, ob1, 0, 0, 0);
;         }
.Lat_loop:
	v_add3_u32 v224, s34, v183, v128
	ds_read_b128 v[212:215], v224 offset:6656
	ds_read_b128 v[216:219], v224 offset:6688
	ds_read_b128 v[220:223], v224 offset:6720
	s_waitcnt lgkmcnt(6)
	v_mfma_f32_32x32x16_bf16 v[16:31], v[196:199], v[96:99], v[16:31]
	v_max3_f32 v226, v64, v65, v66
	v_max3_f32 v236, v80, v81, v82
	v_max3_f32 v227, v67, v68, v69
	v_max3_f32 v237, v83, v84, v85
	s_waitcnt lgkmcnt(5)
	v_mfma_f32_32x32x16_bf16 v[48:63], v[200:203], v[96:99], v[48:63]
	v_max3_f32 v226, v226, v70, v71
	v_max3_f32 v236, v236, v86, v87
	v_max3_f32 v227, v227, v72, v73
	v_max3_f32 v237, v237, v88, v89
	s_waitcnt lgkmcnt(4)
	v_mfma_f32_32x32x16_bf16 v[16:31], v[204:207], v[100:103], v[16:31]
	v_max3_f32 v226, v226, v74, v75
	v_max3_f32 v236, v236, v90, v91
	v_max3_f32 v227, v227, v76, v77
	v_max3_f32 v237, v237, v92, v93
	s_waitcnt lgkmcnt(3)
	v_mfma_f32_32x32x16_bf16 v[48:63], v[208:211], v[100:103], v[48:63]
	v_max3_f32 v226, v226, v78, v79
	v_max3_f32 v236, v236, v94, v95
	v_max_f32_e32 v226, v226, v227
	v_max_f32_e32 v236, v236, v237
	v_cmp_lt_f32_e32 vcc, s33, v226
	s_cbranch_vccnz .Lat_resc_aE
.Lat_back_aE:
	v_exp_f32_e32 v64, v64
	v_mfma_f32_32x32x16_bf16 v[32:47], v[196:199], v[112:115], v[32:47]
	v_exp_f32_e32 v65, v65
	v_exp_f32_e32 v66, v66
	v_exp_f32_e32 v67, v67
	v_exp_f32_e32 v68, v68
	v_mfma_f32_32x32x16_bf16 v[0:15], v[200:203], v[112:115], v[0:15]
	v_exp_f32_e32 v69, v69
	v_add_f32_e32 v230, v64, v65
	v_exp_f32_e32 v70, v70
	v_exp_f32_e32 v71, v71
	v_mfma_f32_32x32x16_bf16 v[32:47], v[204:207], v[116:119], v[32:47]
	v_add_f32_e32 v231, v66, v67
	v_exp_f32_e32 v72, v72
	v_exp_f32_e32 v73, v73
	v_add_f32_e32 v230, v230, v68
	v_mfma_f32_32x32x16_bf16 v[0:15], v[208:211], v[116:119], v[0:15]
	v_add_f32_e32 v231, v231, v69
	v_add3_u32 v225, s34, v187, v128
	ds_read_b128 v[196:199], v225 offset:13312
	ds_read_b128 v[200:203], v225 offset:17920
	ds_read_b128 v[204:207], v225 offset:13344
	ds_read_b128 v[208:211], v225 offset:17952
	v_exp_f32_e32 v74, v74
	v_exp_f32_e32 v75, v75
	v_add_f32_e32 v230, v230, v70
	v_mfma_f32_32x32x16_bf16 v[96:111], v[240:243], v[244:247], 0
	v_add_f32_e32 v231, v231, v71
	v_exp_f32_e32 v76, v76
	v_exp_f32_e32 v77, v77
	v_add_f32_e32 v230, v230, v72
	v_add_f32_e32 v231, v231, v73
	s_waitcnt lgkmcnt(6)
	v_mfma_f32_32x32x16_bf16 v[96:111], v[212:215], v[130:133], v[96:111]
	v_exp_f32_e32 v78, v78
	v_exp_f32_e32 v79, v79
	v_add_f32_e32 v230, v230, v74
	v_add_f32_e32 v231, v231, v75
	v_mfma_f32_32x32x16_bf16 v[112:127], v[212:215], v[138:141], 0
	ds_read_b128 v[212:215], v224 offset:6752
	v_add_f32_e32 v230, v230, v76
	v_add_f32_e32 v231, v231, v77
	v_add_f32_e32 v230, v230, v78
	v_add_f32_e32 v231, v231, v79
	v_add_f32_e32 v230, v230, v231
	s_waitcnt lgkmcnt(6)
	v_mfma_f32_32x32x16_bf16 v[96:111], v[216:219], v[134:137], v[96:111]
	v_add_f32_e32 v191, v191, v230
	v_cvt_pk_bf16_f32 v64, v64, v65
	v_cvt_pk_bf16_f32 v65, v66, v67
	v_cvt_pk_bf16_f32 v66, v68, v69
	v_cvt_pk_bf16_f32 v67, v70, v71
	v_mfma_f32_32x32x16_bf16 v[112:127], v[216:219], v[142:145], v[112:127]
	ds_read_b128 v[216:219], v224 offset:6784
	v_cvt_pk_bf16_f32 v68, v72, v73
	v_cvt_pk_bf16_f32 v69, v74, v75
	v_cvt_pk_bf16_f32 v70, v76, v77
	v_cvt_pk_bf16_f32 v71, v78, v79
	s_waitcnt lgkmcnt(6)
	v_mfma_f32_32x32x16_bf16 v[96:111], v[220:223], v[146:149], v[96:111]
	v_cmp_lt_f32_e32 vcc, s33, v236
	s_cbranch_vccnz .Lat_resc_bE
.Lat_back_bE:
	v_exp_f32_e32 v80, v80
	v_exp_f32_e32 v81, v81
	v_exp_f32_e32 v82, v82
	v_exp_f32_e32 v83, v83
	v_mfma_f32_32x32x16_bf16 v[112:127], v[220:223], v[154:157], v[112:127]
	ds_read_b128 v[220:223], v224 offset:6816
	v_exp_f32_e32 v84, v84
	v_exp_f32_e32 v85, v85
	v_add_f32_e32 v230, v80, v81
	v_exp_f32_e32 v86, v86
	v_exp_f32_e32 v87, v87
	s_waitcnt lgkmcnt(2)
	v_mfma_f32_32x32x16_bf16 v[96:111], v[212:215], v[150:153], v[96:111]
	v_add_f32_e32 v231, v82, v83
	v_exp_f32_e32 v88, v88
	v_exp_f32_e32 v89, v89
	v_add_f32_e32 v230, v230, v84
	v_add_f32_e32 v231, v231, v85
	v_mfma_f32_32x32x16_bf16 v[112:127], v[212:215], v[158:161], v[112:127]
	v_exp_f32_e32 v90, v90
	v_exp_f32_e32 v91, v91
	v_add_f32_e32 v230, v230, v86
	v_add_f32_e32 v231, v231, v87
	s_waitcnt lgkmcnt(1)
	v_mfma_f32_32x32x16_bf16 v[96:111], v[216:219], v[162:165], v[96:111]
	v_exp_f32_e32 v92, v92
	v_exp_f32_e32 v93, v93
	v_add_f32_e32 v230, v230, v88
	v_add_f32_e32 v231, v231, v89
	v_exp_f32_e32 v94, v94
	v_mfma_f32_32x32x16_bf16 v[112:127], v[216:219], v[170:173], v[112:127]
	v_exp_f32_e32 v95, v95
	v_add_f32_e32 v230, v230, v90
	v_add_f32_e32 v231, v231, v91
	v_add_f32_e32 v230, v230, v92
	v_add_f32_e32 v231, v231, v93
	s_waitcnt lgkmcnt(0)
	v_mfma_f32_32x32x16_bf16 v[96:111], v[220:223], v[166:169], v[96:111]
	v_add_f32_e32 v230, v230, v94
	v_add_f32_e32 v231, v231, v95
	v_add_f32_e32 v230, v230, v231
	v_add_f32_e32 v193, v193, v230
	v_mfma_f32_32x32x16_bf16 v[112:127], v[220:223], v[174:177], v[112:127]
	v_cvt_pk_bf16_f32 v80, v80, v81
	v_cvt_pk_bf16_f32 v81, v82, v83
	v_cvt_pk_bf16_f32 v82, v84, v85
	v_cvt_pk_bf16_f32 v83, v86, v87
	v_cvt_pk_bf16_f32 v84, v88, v89
	v_mfma_f32_32x32x16_bf16 v[112:127], v[240:243], v[248:251], v[112:127]
	v_cvt_pk_bf16_f32 v85, v90, v91
	v_cvt_pk_bf16_f32 v86, v92, v93
	v_cvt_pk_bf16_f32 v87, v94, v95
	s_waitcnt vmcnt(0)
	s_barrier
	s_cmpk_gt_u32 s27, 0x81
	s_cbranch_scc1 .Lat_dma_endL
	s_cmp_lt_u32 s27, 2
	s_cselect_b32 s14, s10, s11
	s_add_i32 s14, s14, s24
	s_and_b64 vcc, exec, s[4:5]
	s_cbranch_vccnz .Lat_dmaL_0
	v_mad_u64_u32 v[234:235], s[16:17], v182, s14, v[180:181]
	s_add_i32 m0, s25, s19
	s_nop 0
	global_load_lds_dwordx4 v[234:235], off

; #define LAS __attribute__((address_space(3)))
; #define DMAT(kt, so) do { const unsigned rb_ = (unsigned)ROWBASE(kt); _Pragma("unroll") for (int r = 0; r < 3; ++r) if (wid + 8 * r < 22) \
;         __builtin_amdgcn_global_load_lds((const unsigned*)(dsrc[r] + (size_t)rb_ * dmul[r]), (LAS unsigned*)(lds + (so) + dlds[r]), 16, 0, 0); } while (0)
; __device__ __forceinline__ void attn_unit2(LAS unsigned char* lds, const bf16_t* __restrict__ Q, const bf16_t* __restrict__ KN, const bf16_t* __restrict__ KPE, ...
;     ...
;     for (int t = 0; t < ntiles; ++t) {
;         __builtin_amdgcn_sched_barrier(0);
;         f32x16 sa0 = {}, sa1 = {}, sb0 = {}, sb1 = {};
;         const LAS unsigned char* ka = lds + sc + ka_off;
; #pragma unroll
;         for (int ds = 0; ds < 6; ++ds) {
;             const bf16x8 k0 = *(const LAS bf16x8*)(ka + ds * 32);
;             const bf16x8 k1 = *(const LAS bf16x8*)(ka + 32 * KROW + ds * 32);
;             sa0 = __builtin_amdgcn_mfma_f32_32x32x16_bf16(k0, qa[ds], sa0, 0, 0, 0);
;             sa1 = __builtin_amdgcn_mfma_f32_32x32x16_bf16(k1, qa[ds], sa1, 0, 0, 0);
;             sb0 = __builtin_amdgcn_mfma_f32_32x32x16_bf16(k0, qb[ds], sb0, 0, 0, 0);
;             sb1 = __builtin_amdgcn_mfma_f32_32x32x16_bf16(k1, qb[ds], sb1, 0, 0, 0);
;         }
;         __builtin_amdgcn_sched_barrier(0);
;         if (t + 2 < ntiles) DMAT(t + 2, snn);
;         u32x4 pa[4], pb[4];
;     ...
;         SOFTMAX2(sa0, sa1, ma, la, oa0, oa1, pa);
;         SOFTMAX2(sb0, sb1, mb, lb, ob0, ob1, pb);
;     ...
;         const LAS unsigned char* va = lds + sc + va_off;
; #pragma unroll
;         for (int st = 0; st < 4; ++st) {
;             const bf16x8 v0 = *(const LAS bf16x8*)(va + st * 32);
;             const bf16x8 v1 = *(const LAS bf16x8*)(va + 32 * VROW + st * 32);
;             const bf16x8 fa = __builtin_bit_cast(bf16x8, pa[st]), fb = __builtin_bit_cast(bf16x8, pb[st]);
;             oa0 = __builtin_amdgcn_mfma_f32_32x32x16_bf16(v0, fa, oa0, 0, 0, 0);
;             oa1 = __builtin_amdgcn_mfma_f32_32x32x16_bf16(v1, fa, oa1, 0, 0, 0);
;             ob0 = __builtin_amdgcn_mfma_f32_32x32x16_bf16(v0, fb, ob0, 0, 0, 0);
;             ob1 = __builtin_amdgcn_mfma_f32_32x32x16_bf16(v1, fb, ob1, 0, 0, 0);
;         }
;         __builtin_amdgcn_sched_barrier(0);
;         __syncthreads();
;         { const int tmp = sc; sc = sn; sn = snn; snn = tmp; }
.Lat_dmaL_2:
.Lat_dma_endL:
	v_add3_u32 v224, s26, v183, v128
	ds_read_b128 v[212:215], v224 offset:0
	ds_read_b128 v[216:219], v224 offset:32
	ds_read_b128 v[220:223], v224 offset:64
	v_mfma_f32_32x32x16_bf16 v[16:31], v[196:199], v[64:67], v[16:31]
	v_max3_f32 v226, v96, v97, v98
	v_max3_f32 v236, v112, v113, v114
	v_max3_f32 v227, v99, v100, v101
	v_max3_f32 v237, v115, v116, v117
	v_mfma_f32_32x32x16_bf16 v[48:63], v[200:203], v[64:67], v[48:63]
	v_max3_f32 v226, v226, v102, v103
	v_max3_f32 v236, v236, v118, v119
	v_max3_f32 v227, v227, v104, v105
	v_max3_f32 v237, v237, v120, v121
	v_mfma_f32_32x32x16_bf16 v[16:31], v[204:207], v[68:71], v[16:31]
	v_max3_f32 v226, v226, v106, v107
	v_max3_f32 v236, v236, v122, v123
	v_max3_f32 v227, v227, v108, v109
	v_max3_f32 v237, v237, v124, v125
	v_mfma_f32_32x32x16_bf16 v[48:63], v[208:211], v[68:71], v[48:63]
	v_max3_f32 v226, v226, v110, v111
	v_max3_f32 v236, v236, v126, v127
	v_max_f32_e32 v226, v226, v227
	v_max_f32_e32 v236, v236, v237
	v_cmp_lt_f32_e32 vcc, s33, v226
	s_cbranch_vccnz .Lat_resc_aO
.Lat_back_aO:
	v_exp_f32_e32 v96, v96
	v_mfma_f32_32x32x16_bf16 v[32:47], v[196:199], v[80:83], v[32:47]
	v_exp_f32_e32 v97, v97
	v_exp_f32_e32 v98, v98
	v_exp_f32_e32 v99, v99
	v_exp_f32_e32 v100, v100
	v_mfma_f32_32x32x16_bf16 v[0:15], v[200:203], v[80:83], v[0:15]
	v_exp_f32_e32 v101, v101
	v_add_f32_e32 v230, v96, v97
	v_exp_f32_e32 v102, v102
	v_exp_f32_e32 v103, v103
	v_mfma_f32_32x32x16_bf16 v[32:47], v[204:207], v[84:87], v[32:47]
	v_add_f32_e32 v231, v98, v99
	v_exp_f32_e32 v104, v104
	v_exp_f32_e32 v105, v105
	v_add_f32_e32 v230, v230, v100
	v_mfma_f32_32x32x16_bf16 v[0:15], v[208:211], v[84:87], v[0:15]
	v_add_f32_e32 v231, v231, v101
	v_add3_u32 v225, s34, v187, v128
	ds_read_b128 v[196:199], v225 offset:13376
	ds_read_b128 v[200:203], v225 offset:17984
	ds_read_b128 v[204:207], v225 offset:13408
	ds_read_b128 v[208:211], v225 offset:18016
	v_exp_f32_e32 v106, v106
	v_exp_f32_e32 v107, v107
	v_add_f32_e32 v230, v230, v102
	v_mfma_f32_32x32x16_bf16 v[64:79], v[240:243], v[244:247], 0
	v_add_f32_e32 v231, v231, v103
	v_exp_f32_e32 v108, v108
	v_exp_f32_e32 v109, v109
	v_add_f32_e32 v230, v230, v104
	v_add_f32_e32 v231, v231, v105
	s_waitcnt lgkmcnt(6)
	v_mfma_f32_32x32x16_bf16 v[64:79], v[212:215], v[130:133], v[64:79]
	v_exp_f32_e32 v110, v110
	v_exp_f32_e32 v111, v111
	v_add_f32_e32 v230, v230, v106
	v_add_f32_e32 v231, v231, v107
	v_mfma_f32_32x32x16_bf16 v[80:95], v[212:215], v[138:141], 0
	ds_read_b128 v[212:215], v224 offset:96
	v_add_f32_e32 v230, v230, v108
	v_add_f32_e32 v231, v231, v109
	v_add_f32_e32 v230, v230, v110
	v_add_f32_e32 v231, v231, v111
	v_add_f32_e32 v230, v230, v231
	s_waitcnt lgkmcnt(6)
	v_mfma_f32_32x32x16_bf16 v[64:79], v[216:219], v[134:137], v[64:79]
	v_add_f32_e32 v191, v191, v230
	v_cvt_pk_bf16_f32 v96, v96, v97
	v_cvt_pk_bf16_f32 v97, v98, v99
	v_cvt_pk_bf16_f32 v98, v100, v101
	v_cvt_pk_bf16_f32 v99, v102, v103
	v_mfma_f32_32x32x16_bf16 v[80:95], v[216:219], v[142:145], v[80:95]
	ds_read_b128 v[216:219], v224 offset:128
	v_cvt_pk_bf16_f32 v100, v104, v105
	v_cvt_pk_bf16_f32 v101, v106, v107
	v_cvt_pk_bf16_f32 v102, v108, v109
	v_cvt_pk_bf16_f32 v103, v110, v111
	s_waitcnt lgkmcnt(6)
	v_mfma_f32_32x32x16_bf16 v[64:79], v[220:223], v[146:149], v[64:79]
	v_cmp_lt_f32_e32 vcc, s33, v236
	s_cbranch_vccnz .Lat_resc_bO
.Lat_back_bO:
	v_exp_f32_e32 v112, v112
	v_exp_f32_e32 v113, v113
	v_exp_f32_e32 v114, v114
	v_exp_f32_e32 v115, v115
	v_mfma_f32_32x32x16_bf16 v[80:95], v[220:223], v[154:157], v[80:95]
	ds_read_b128 v[220:223], v224 offset:160
	v_exp_f32_e32 v116, v116
	v_exp_f32_e32 v117, v117
	v_add_f32_e32 v230, v112, v113
	v_exp_f32_e32 v118, v118
	v_exp_f32_e32 v119, v119
	s_waitcnt lgkmcnt(2)
	v_mfma_f32_32x32x16_bf16 v[64:79], v[212:215], v[150:153], v[64:79]
	v_add_f32_e32 v231, v114, v115
	v_exp_f32_e32 v120, v120
	v_exp_f32_e32 v121, v121
	v_add_f32_e32 v230, v230, v116
	v_add_f32_e32 v231, v231, v117
	v_mfma_f32_32x32x16_bf16 v[80:95], v[212:215], v[158:161], v[80:95]
	v_exp_f32_e32 v122, v122
	v_exp_f32_e32 v123, v123
	v_add_f32_e32 v230, v230, v118
	v_add_f32_e32 v231, v231, v119
	s_waitcnt lgkmcnt(1)
	v_mfma_f32_32x32x16_bf16 v[64:79], v[216:219], v[162:165], v[64:79]
	v_exp_f32_e32 v124, v124
	v_exp_f32_e32 v125, v125
	v_add_f32_e32 v230, v230, v120
	v_add_f32_e32 v231, v231, v121
	v_exp_f32_e32 v126, v126
	v_mfma_f32_32x32x16_bf16 v[80:95], v[216:219], v[170:173], v[80:95]
	v_exp_f32_e32 v127, v127
	v_add_f32_e32 v230, v230, v122
	v_add_f32_e32 v231, v231, v123
	v_add_f32_e32 v230, v230, v124
	v_add_f32_e32 v231, v231, v125
	s_waitcnt lgkmcnt(0)
	v_mfma_f32_32x32x16_bf16 v[64:79], v[220:223], v[166:169], v[64:79]
	v_add_f32_e32 v230, v230, v126
	v_add_f32_e32 v231, v231, v127
	v_add_f32_e32 v230, v230, v231
	v_add_f32_e32 v193, v193, v230
	v_mfma_f32_32x32x16_bf16 v[80:95], v[220:223], v[174:177], v[80:95]
	v_cvt_pk_bf16_f32 v112, v112, v113
	v_cvt_pk_bf16_f32 v113, v114, v115
	v_cvt_pk_bf16_f32 v114, v116, v117
	v_cvt_pk_bf16_f32 v115, v118, v119
	v_cvt_pk_bf16_f32 v116, v120, v121
	v_mfma_f32_32x32x16_bf16 v[80:95], v[240:243], v[248:251], v[80:95]
	v_cvt_pk_bf16_f32 v117, v122, v123
	v_cvt_pk_bf16_f32 v118, v124, v125
	v_cvt_pk_bf16_f32 v119, v126, v127
	s_add_i32 s27, s27, 1
	s_add_i32 s24, s24, 64
	s_mov_b32 s14, s34
	s_mov_b32 s34, s26
	s_mov_b32 s26, s25
	s_mov_b32 s25, s14
	s_cmpk_lg_i32 s27, 0x84
	s_cbranch_scc1 .Lat_loop
	s_waitcnt lgkmcnt(3)
	v_mfma_f32_32x32x16_bf16 v[16:31], v[196:199], v[96:99], v[16:31]
	s_waitcnt lgkmcnt(2)
	v_mfma_f32_32x32x16_bf16 v[48:63], v[200:203], v[96:99], v[48:63]
	s_waitcnt lgkmcnt(1)
	v_mfma_f32_32x32x16_bf16 v[16:31], v[204:207], v[100:103], v[16:31]
	s_waitcnt lgkmcnt(0)
	v_mfma_f32_32x32x16_bf16 v[48:63], v[208:211], v[100:103], v[48:63]
	v_mfma_f32_32x32x16_bf16 v[32:47], v[196:199], v[112:115], v[32:47]
	v_mfma_f32_32x32x16_bf16 v[0:15], v[200:203], v[112:115], v[0:15]
	v_mfma_f32_32x32x16_bf16 v[32:47], v[204:207], v[116:119], v[32:47]
	v_mfma_f32_32x32x16_bf16 v[0:15], v[208:211], v[116:119], v[0:15]
	s_branch .Lat_done

.Lat_resc_bE:
	s_nop 15
	v_mov_b32_e32 v237, v236
	s_nop 1
	v_permlane32_swap_b32_e32 v236, v237
	v_max_f32_e32 v236, v236, v237
	v_max_f32_e32 v236, 0, v236
	v_add_f32_e32 v237, v195, v236
	v_cvt_pk_bf16_f32 v237, v237, v237
	v_and_b32_e32 v237, 0xffff0000, v237
	v_sub_f32_e32 v229, v195, v237
	v_mov_b32_e32 v195, v237
	v_exp_f32_e32 v232, v229
	v_add_f32_e32 v80, v80, v229
	v_add_f32_e32 v81, v81, v229
	v_add_f32_e32 v82, v82, v229
	v_add_f32_e32 v83, v83, v229
	v_add_f32_e32 v84, v84, v229
	v_add_f32_e32 v85, v85, v229
	v_add_f32_e32 v86, v86, v229
	v_add_f32_e32 v87, v87, v229
	v_add_f32_e32 v88, v88, v229
	v_add_f32_e32 v89, v89, v229
	v_add_f32_e32 v90, v90, v229
	v_add_f32_e32 v91, v91, v229
	v_add_f32_e32 v92, v92, v229
	v_add_f32_e32 v93, v93, v229
	v_add_f32_e32 v94, v94, v229
	v_add_f32_e32 v95, v95, v229
	v_xor_b32_e32 v237, 0x80000000, v237
	v_lshrrev_b32_e32 v237, 16, v237
	v_and_b32_e32 v248, v228, v237
	v_pk_mul_f32 v[32:33], v[32:33], v[232:233] op_sel_hi:[1,0]
	v_pk_mul_f32 v[34:35], v[34:35], v[232:233] op_sel_hi:[1,0]
	v_pk_mul_f32 v[36:37], v[36:37], v[232:233] op_sel_hi:[1,0]
	v_pk_mul_f32 v[38:39], v[38:39], v[232:233] op_sel_hi:[1,0]
	v_pk_mul_f32 v[40:41], v[40:41], v[232:233] op_sel_hi:[1,0]
	v_pk_mul_f32 v[42:43], v[42:43], v[232:233] op_sel_hi:[1,0]
	v_pk_mul_f32 v[44:45], v[44:45], v[232:233] op_sel_hi:[1,0]
	v_pk_mul_f32 v[46:47], v[46:47], v[232:233] op_sel_hi:[1,0]
	v_pk_mul_f32 v[0:1], v[0:1], v[232:233] op_sel_hi:[1,0]
	v_pk_mul_f32 v[2:3], v[2:3], v[232:233] op_sel_hi:[1,0]
	v_pk_mul_f32 v[4:5], v[4:5], v[232:233] op_sel_hi:[1,0]
	v_pk_mul_f32 v[6:7], v[6:7], v[232:233] op_sel_hi:[1,0]
	v_pk_mul_f32 v[8:9], v[8:9], v[232:233] op_sel_hi:[1,0]
	v_pk_mul_f32 v[10:11], v[10:11], v[232:233] op_sel_hi:[1,0]
	v_pk_mul_f32 v[12:13], v[12:13], v[232:233] op_sel_hi:[1,0]
	v_pk_mul_f32 v[14:15], v[14:15], v[232:233] op_sel_hi:[1,0]
	v_mul_f32_e32 v193, v193, v232
	s_branch .Lat_back_bE

.Lat_resc_bO:
	s_nop 15
	v_mov_b32_e32 v237, v236
	s_nop 1
	v_permlane32_swap_b32_e32 v236, v237
	v_max_f32_e32 v236, v236, v237
	v_max_f32_e32 v236, 0, v236
	v_add_f32_e32 v237, v195, v236
	v_cvt_pk_bf16_f32 v237, v237, v237
	v_and_b32_e32 v237, 0xffff0000, v237
	v_sub_f32_e32 v229, v195, v237
	v_mov_b32_e32 v195, v237
	v_exp_f32_e32 v232, v229
	v_add_f32_e32 v112, v112, v229
	v_add_f32_e32 v113, v113, v229
	v_add_f32_e32 v114, v114, v229
	v_add_f32_e32 v115, v115, v229
	v_add_f32_e32 v116, v116, v229
	v_add_f32_e32 v117, v117, v229
	v_add_f32_e32 v118, v118, v229
	v_add_f32_e32 v119, v119, v229
	v_add_f32_e32 v120, v120, v229
	v_add_f32_e32 v121, v121, v229
	v_add_f32_e32 v122, v122, v229
	v_add_f32_e32 v123, v123, v229
	v_add_f32_e32 v124, v124, v229
	v_add_f32_e32 v125, v125, v229
	v_add_f32_e32 v126, v126, v229
	v_add_f32_e32 v127, v127, v229
	v_xor_b32_e32 v237, 0x80000000, v237
	v_lshrrev_b32_e32 v237, 16, v237
	v_and_b32_e32 v248, v228, v237
	v_pk_mul_f32 v[32:33], v[32:33], v[232:233] op_sel_hi:[1,0]
	v_pk_mul_f32 v[34:35], v[34:35], v[232:233] op_sel_hi:[1,0]
	v_pk_mul_f32 v[36:37], v[36:37], v[232:233] op_sel_hi:[1,0]
	v_pk_mul_f32 v[38:39], v[38:39], v[232:233] op_sel_hi:[1,0]
	v_pk_mul_f32 v[40:41], v[40:41], v[232:233] op_sel_hi:[1,0]
	v_pk_mul_f32 v[42:43], v[42:43], v[232:233] op_sel_hi:[1,0]
	v_pk_mul_f32 v[44:45], v[44:45], v[232:233] op_sel_hi:[1,0]
	v_pk_mul_f32 v[46:47], v[46:47], v[232:233] op_sel_hi:[1,0]
	v_pk_mul_f32 v[0:1], v[0:1], v[232:233] op_sel_hi:[1,0]
	v_pk_mul_f32 v[2:3], v[2:3], v[232:233] op_sel_hi:[1,0]
	v_pk_mul_f32 v[4:5], v[4:5], v[232:233] op_sel_hi:[1,0]
	v_pk_mul_f32 v[6:7], v[6:7], v[232:233] op_sel_hi:[1,0]
	v_pk_mul_f32 v[8:9], v[8:9], v[232:233] op_sel_hi:[1,0]
	v_pk_mul_f32 v[10:11], v[10:11], v[232:233] op_sel_hi:[1,0]
	v_pk_mul_f32 v[12:13], v[12:13], v[232:233] op_sel_hi:[1,0]
	v_pk_mul_f32 v[14:15], v[14:15], v[232:233] op_sel_hi:[1,0]
	v_mul_f32_e32 v193, v193, v232
	s_branch .Lat_back_bO
